# v10 + phase D select: count pass with prefetched LDS reads (verified against the original counts in a side build)
# speedup vs baseline: 1.0290x; 1.0016x over previous
.LBB0_692:
	s_or_b64 exec, exec, s[22:23]
	v_mov_b32_e32 v1, 0
	v_mov_b32_e32 v0, 0
	s_and_saveexec_b64 s[30:31], s[0:1]
	s_cbranch_execz .LBB0_702
	v_add_u32_e32 v2, v9, v194
	v_mov_b32_e32 v3, v145
	ds_read_b128 v[18:21], v2
.Lcn_loop:
	s_waitcnt lgkmcnt(0)
	v_mov_b32_e32 v22, v18
	v_mov_b32_e32 v23, v19
	v_mov_b32_e32 v24, v20
	v_mov_b32_e32 v25, v21
	v_add_u32_e32 v2, 0x400, v2
	ds_read_b128 v[18:21], v2
	v_cmp_ge_u32_e64 s[20:21], v22, v4
	v_cmp_ge_u32_e64 s[34:35], v22, v6
	v_cmp_ge_u32_e64 s[22:23], v23, v4
	v_cmp_ge_u32_e64 s[36:37], v23, v6
	v_cmp_ge_u32_e64 s[24:25], v24, v4
	v_cmp_ge_u32_e64 s[38:39], v24, v6
	v_cmp_ge_u32_e64 s[26:27], v25, v4
	v_cmp_ge_u32_e64 s[40:41], v25, v6
	v_addc_co_u32_e64 v0, s[20:21], 0, v0, s[20:21]
	v_addc_co_u32_e64 v1, s[34:35], 0, v1, s[34:35]
	v_addc_co_u32_e64 v0, s[22:23], 0, v0, s[22:23]
	v_addc_co_u32_e64 v1, s[36:37], 0, v1, s[36:37]
	v_addc_co_u32_e64 v0, s[24:25], 0, v0, s[24:25]
	v_addc_co_u32_e64 v1, s[38:39], 0, v1, s[38:39]
	v_addc_co_u32_e64 v0, s[26:27], 0, v0, s[26:27]
	v_addc_co_u32_e64 v1, s[40:41], 0, v1, s[40:41]
	v_add_u32_e32 v3, 0x100, v3
	v_cmp_lt_u32_e64 s[64:65], v3, v5
	s_nop 0
	s_mov_b64 exec, s[64:65]
	s_cbranch_execnz .Lcn_loop
	s_waitcnt lgkmcnt(0)
